# attention tile loop: next K/V tile LDS writes issued right after sub-step 1's fragment reads and the per-tile barrier moved there (overlaps LDS write time with compute)
# speedup vs baseline: 1.0147x; 1.0147x over previous
; __device__ __forceinline__ unsigned pk2(float lo, float hi) { return pg8::cvt_pk_bf16(lo, hi); }
; #define MFMA32(a, b, c) __builtin_amdgcn_mfma_f32_32x32x16_bf16((a), (b), (c), 0, 0, 0)
; __device__ __forceinline__ void attn_phase(const Args& a, int l, bool with_ctx, unsigned char* lds) {
;     ...
;                 float ps = 0.f;
; #pragma unroll
;                 for (int r = 0; r < 16; ++r) { S[r] = __builtin_amdgcn_exp2f(S[r]); ps += S[r]; }
;                 lrun += ps;
;                 u32x4 p0, p1;
;                 p0.x = pk2(S[0], S[1]); p0.y = pk2(S[2], S[3]); p0.z = pk2(S[4], S[5]); p0.w = pk2(S[6], S[7]);
;                 p1.x = pk2(S[8], S[9]); p1.y = pk2(S[10], S[11]); p1.z = pk2(S[12], S[13]); p1.w = pk2(S[14], S[15]);
;                 const bf16x8 pa0 = __builtin_bit_cast(bf16x8, p0), pa1 = __builtin_bit_cast(bf16x8, p1);
; #pragma unroll
;                 for (int j = 0; j < 4; ++j) O[j] = MFMA32(vf[2 * j], pa0, O[j]);
; #pragma unroll
;                 for (int j = 0; j < 4; ++j) O[j] = MFMA32(vf[2 * j + 1], pa1, O[j]);
;             }
;             if (t + 1 < nt) { unsigned char* kd = kdst + (cur ^ 1) * BUF; unsigned char* vd = vdst + (cur ^ 1) * BUF;
;                 *(u32x4*)kd = k0; *(u32x4*)(kd + 9216) = k1; *(u32x4*)vd = v0; *(u32x4*)(vd + 9216) = v1; }
.LBB0_410:
	v_exp_f32_e32 v67, v68
	v_exp_f32_e32 v186, v69
	v_exp_f32_e32 v187, v70
	v_exp_f32_e32 v213, v71
	v_exp_f32_e32 v214, v72
	v_exp_f32_e32 v215, v73
	v_exp_f32_e32 v216, v74
	v_exp_f32_e32 v217, v75
	v_cvt_pk_bf16_f32 v68, v67, v186
	v_cvt_pk_bf16_f32 v69, v187, v213
	v_cvt_pk_bf16_f32 v70, v214, v215
	v_cvt_pk_bf16_f32 v71, v216, v217
	v_add_f32_e32 v67, 0, v67
	v_add_f32_e32 v67, v186, v67
	s_waitcnt lgkmcnt(7)
	v_mfma_f32_32x32x16_bf16 v[50:65], v[140:143], v[68:71], v[50:65]
	v_exp_f32_e32 v76, v76
	v_exp_f32_e32 v77, v77
	v_exp_f32_e32 v78, v78
	v_exp_f32_e32 v79, v79
	v_exp_f32_e32 v80, v80
	v_exp_f32_e32 v81, v81
	v_exp_f32_e32 v82, v82
	s_waitcnt lgkmcnt(5)
	v_mfma_f32_32x32x16_bf16 v[34:49], v[144:147], v[68:71], v[34:49]
	v_exp_f32_e32 v83, v83
	v_add_f32_e32 v67, v187, v67
	v_add_f32_e32 v67, v213, v67
	v_add_f32_e32 v67, v214, v67
	v_add_f32_e32 v67, v215, v67
	v_cvt_pk_bf16_f32 v72, v76, v77
	v_cvt_pk_bf16_f32 v73, v78, v79
	s_waitcnt lgkmcnt(3)
	v_mfma_f32_32x32x16_bf16 v[18:33], v[136:139], v[68:71], v[18:33]
	v_cvt_pk_bf16_f32 v74, v80, v81
	v_cvt_pk_bf16_f32 v75, v82, v83
	v_add_f32_e32 v67, v216, v67
	v_add_f32_e32 v67, v217, v67
	v_add_f32_e32 v67, v76, v67
	v_add_f32_e32 v67, v77, v67
	v_add_f32_e32 v67, v78, v67
	s_waitcnt lgkmcnt(1)
	v_mfma_f32_32x32x16_bf16 v[2:17], v[132:135], v[68:71], v[2:17]
	v_add_f32_e32 v67, v79, v67
	v_add_f32_e32 v67, v80, v67
	v_add_f32_e32 v67, v81, v67
	v_add_f32_e32 v67, v82, v67
	v_add_f32_e32 v67, v83, v67
	v_add_f32_e32 v171, v171, v67
	v_mfma_f32_32x32x16_bf16 v[50:65], v[128:131], v[72:75], v[50:65]
	v_mfma_f32_32x32x16_bf16 v[34:49], v[116:119], v[72:75], v[34:49]
	v_mfma_f32_32x32x16_bf16 v[18:33], v[120:123], v[72:75], v[18:33]
	s_waitcnt lgkmcnt(0)
	v_mfma_f32_32x32x16_bf16 v[2:17], v[124:127], v[72:75], v[2:17]
	ds_read_b128 v[214:217], v185 offset:4608
	ds_read_b128 v[218:221], v185 offset:4640
	ds_read_b128 v[222:225], v185 offset:4672
	ds_read_b128 v[226:229], v185 offset:4704
	ds_read_b128 v[136:139], v184 offset:18496
	ds_read_b128 v[116:119], v184 offset:18528
	ds_read_b128 v[140:143], v184 offset:23104
	ds_read_b128 v[120:123], v184 offset:23136
	ds_read_b128 v[144:147], v184 offset:27712
	ds_read_b128 v[124:127], v184 offset:27744
	ds_read_b128 v[132:135], v184 offset:32320
	ds_read_b128 v[128:131], v184 offset:32352
	s_xor_b32 s22, s15, 1
	s_mul_i32 s22, s22, 0x9000
	v_add_u32_e32 v246, s22, v176
	s_waitcnt vmcnt(3)
	ds_write_b128 v246, v[100:103]
	s_waitcnt vmcnt(2)
	ds_write_b128 v246, v[104:107] offset:9216
	s_waitcnt vmcnt(1)
	ds_write_b128 v246, v[108:111] offset:18432
	s_waitcnt vmcnt(0)
	ds_write_b128 v246, v[112:115] offset:27648
	s_waitcnt lgkmcnt(15)
	s_nop 0
	v_mfma_f32_32x32x16_bf16 v[68:83], v[214:217], v[84:87], v[230:245]
	s_waitcnt lgkmcnt(14)
	v_mfma_f32_32x32x16_bf16 v[68:83], v[218:221], v[88:91], v[68:83]
	s_waitcnt lgkmcnt(13)
	v_mfma_f32_32x32x16_bf16 v[68:83], v[222:225], v[92:95], v[68:83]
	s_waitcnt lgkmcnt(12)
	v_mfma_f32_32x32x16_bf16 v[68:83], v[226:229], v[96:99], v[68:83]
	s_nop 11
	v_max_f32_e32 v67, v69, v69
	v_max_f32_e32 v184, v68, v68
	v_max_f32_e32 v67, v184, v67
	v_max3_f32 v67, v67, v70, v71
	v_max3_f32 v67, v67, v72, v73
	v_max3_f32 v67, v67, v74, v75
	v_max3_f32 v67, v67, v76, v77
	v_max3_f32 v67, v67, v78, v79
	v_max3_f32 v67, v67, v80, v81
	v_max3_f32 v67, v67, v82, v83
	v_cmp_lt_f32_e32 vcc, s68, v67
	s_cbranch_vccz .LBB0_412
	ds_bpermute_b32 v184, v180, v67
	s_waitcnt lgkmcnt(0)
	v_max3_f32 v184, v67, v184, 0
	v_exp_f32_e64 v186, -v184
	v_sub_f32_e32 v66, v66, v184
	v_mov_b32_e32 v230, v66
	v_mov_b32_e32 v231, v66
	v_mov_b32_e32 v232, v66
	v_mov_b32_e32 v233, v66
	v_mov_b32_e32 v234, v66
	v_mov_b32_e32 v235, v66
	v_mov_b32_e32 v236, v66
	v_mov_b32_e32 v237, v66
	v_mov_b32_e32 v238, v66
	v_mov_b32_e32 v239, v66
	v_mov_b32_e32 v240, v66
	v_mov_b32_e32 v241, v66
	v_mov_b32_e32 v242, v66
	v_mov_b32_e32 v243, v66
	v_mov_b32_e32 v244, v66
	v_mov_b32_e32 v245, v66
	v_pk_add_f32 v[68:69], v[68:69], v[184:185] op_sel_hi:[1,0] neg_lo:[0,1] neg_hi:[0,1]
	v_pk_add_f32 v[70:71], v[70:71], v[184:185] op_sel_hi:[1,0] neg_lo:[0,1] neg_hi:[0,1]
	v_pk_add_f32 v[72:73], v[72:73], v[184:185] op_sel_hi:[1,0] neg_lo:[0,1] neg_hi:[0,1]
	v_pk_add_f32 v[74:75], v[74:75], v[184:185] op_sel_hi:[1,0] neg_lo:[0,1] neg_hi:[0,1]
	v_pk_add_f32 v[76:77], v[76:77], v[184:185] op_sel_hi:[1,0] neg_lo:[0,1] neg_hi:[0,1]
	v_pk_add_f32 v[78:79], v[78:79], v[184:185] op_sel_hi:[1,0] neg_lo:[0,1] neg_hi:[0,1]
	v_pk_add_f32 v[80:81], v[80:81], v[184:185] op_sel_hi:[1,0] neg_lo:[0,1] neg_hi:[0,1]
	v_pk_add_f32 v[82:83], v[82:83], v[184:185] op_sel_hi:[1,0] neg_lo:[0,1] neg_hi:[0,1]
	v_pk_mul_f32 v[64:65], v[64:65], v[186:187] op_sel_hi:[1,0]
	v_pk_mul_f32 v[62:63], v[62:63], v[186:187] op_sel_hi:[1,0]
	v_pk_mul_f32 v[60:61], v[60:61], v[186:187] op_sel_hi:[1,0]
	v_pk_mul_f32 v[58:59], v[58:59], v[186:187] op_sel_hi:[1,0]
	v_pk_mul_f32 v[56:57], v[56:57], v[186:187] op_sel_hi:[1,0]
	v_pk_mul_f32 v[54:55], v[54:55], v[186:187] op_sel_hi:[1,0]
	v_pk_mul_f32 v[52:53], v[52:53], v[186:187] op_sel_hi:[1,0]
	v_pk_mul_f32 v[50:51], v[50:51], v[186:187] op_sel_hi:[1,0]
	v_pk_mul_f32 v[48:49], v[48:49], v[186:187] op_sel_hi:[1,0]
	v_pk_mul_f32 v[46:47], v[46:47], v[186:187] op_sel_hi:[1,0]
	v_pk_mul_f32 v[44:45], v[44:45], v[186:187] op_sel_hi:[1,0]
	v_pk_mul_f32 v[42:43], v[42:43], v[186:187] op_sel_hi:[1,0]
	v_pk_mul_f32 v[40:41], v[40:41], v[186:187] op_sel_hi:[1,0]
	v_pk_mul_f32 v[38:39], v[38:39], v[186:187] op_sel_hi:[1,0]
	v_pk_mul_f32 v[36:37], v[36:37], v[186:187] op_sel_hi:[1,0]
	v_pk_mul_f32 v[34:35], v[34:35], v[186:187] op_sel_hi:[1,0]
	v_pk_mul_f32 v[32:33], v[32:33], v[186:187] op_sel_hi:[1,0]
	v_pk_mul_f32 v[30:31], v[30:31], v[186:187] op_sel_hi:[1,0]
	v_pk_mul_f32 v[28:29], v[28:29], v[186:187] op_sel_hi:[1,0]
	v_pk_mul_f32 v[26:27], v[26:27], v[186:187] op_sel_hi:[1,0]
	v_pk_mul_f32 v[24:25], v[24:25], v[186:187] op_sel_hi:[1,0]
	v_pk_mul_f32 v[22:23], v[22:23], v[186:187] op_sel_hi:[1,0]
	v_pk_mul_f32 v[20:21], v[20:21], v[186:187] op_sel_hi:[1,0]
	v_pk_mul_f32 v[18:19], v[18:19], v[186:187] op_sel_hi:[1,0]
	v_pk_mul_f32 v[16:17], v[16:17], v[186:187] op_sel_hi:[1,0]
	v_pk_mul_f32 v[14:15], v[14:15], v[186:187] op_sel_hi:[1,0]
	v_pk_mul_f32 v[12:13], v[12:13], v[186:187] op_sel_hi:[1,0]
	v_pk_mul_f32 v[10:11], v[10:11], v[186:187] op_sel_hi:[1,0]
	v_pk_mul_f32 v[8:9], v[8:9], v[186:187] op_sel_hi:[1,0]
	v_pk_mul_f32 v[6:7], v[6:7], v[186:187] op_sel_hi:[1,0]
	v_pk_mul_f32 v[4:5], v[4:5], v[186:187] op_sel_hi:[1,0]
	v_pk_mul_f32 v[2:3], v[2:3], v[186:187] op_sel_hi:[1,0]
	v_mul_f32_e32 v171, v171, v186
; __device__ __forceinline__ unsigned pk2(float lo, float hi) { return pg8::cvt_pk_bf16(lo, hi); }
; #define MFMA32(a, b, c) __builtin_amdgcn_mfma_f32_32x32x16_bf16((a), (b), (c), 0, 0, 0)
; __device__ __forceinline__ void attn_phase(const Args& a, int l, bool with_ctx, unsigned char* lds) {
;     ...
;                 float ps = 0.f;
; #pragma unroll
;                 for (int r = 0; r < 16; ++r) { S[r] = __builtin_amdgcn_exp2f(S[r]); ps += S[r]; }
;                 lrun += ps;
;                 u32x4 p0, p1;
;                 p0.x = pk2(S[0], S[1]); p0.y = pk2(S[2], S[3]); p0.z = pk2(S[4], S[5]); p0.w = pk2(S[6], S[7]);
;                 p1.x = pk2(S[8], S[9]); p1.y = pk2(S[10], S[11]); p1.z = pk2(S[12], S[13]); p1.w = pk2(S[14], S[15]);
;                 const bf16x8 pa0 = __builtin_bit_cast(bf16x8, p0), pa1 = __builtin_bit_cast(bf16x8, p1);
; #pragma unroll
;                 for (int j = 0; j < 4; ++j) O[j] = MFMA32(vf[2 * j], pa0, O[j]);
; #pragma unroll
;                 for (int j = 0; j < 4; ++j) O[j] = MFMA32(vf[2 * j + 1], pa1, O[j]);
;             }
;             if (t + 1 < nt) { unsigned char* kd = kdst + (cur ^ 1) * BUF; unsigned char* vd = vdst + (cur ^ 1) * BUF;
;                 *(u32x4*)kd = k0; *(u32x4*)(kd + 9216) = k1; *(u32x4*)vd = v0; *(u32x4*)(vd + 9216) = v1; }
;             __syncthreads();
.LBB0_412:
	s_waitcnt lgkmcnt(0)
	s_barrier
	v_exp_f32_e32 v67, v68
	v_exp_f32_e32 v68, v69
	v_exp_f32_e32 v69, v70
	v_exp_f32_e32 v70, v71
	v_exp_f32_e32 v71, v72
	v_exp_f32_e32 v72, v73
	v_exp_f32_e32 v73, v74
	v_exp_f32_e32 v74, v75
	v_cvt_pk_bf16_f32 v184, v67, v68
	v_cvt_pk_bf16_f32 v185, v69, v70
	v_cvt_pk_bf16_f32 v186, v71, v72
	v_cvt_pk_bf16_f32 v187, v73, v74
	v_exp_f32_e32 v75, v76
	v_exp_f32_e32 v76, v77
	s_waitcnt lgkmcnt(11)
	v_mfma_f32_32x32x16_bf16 v[50:65], v[136:139], v[184:187], v[50:65]
	v_exp_f32_e32 v77, v78
	v_exp_f32_e32 v78, v79
	v_exp_f32_e32 v79, v80
	v_exp_f32_e32 v80, v81
	v_exp_f32_e32 v81, v82
	v_exp_f32_e32 v82, v83
	v_cvt_pk_bf16_f32 v214, v75, v76
	s_waitcnt lgkmcnt(9)
	v_mfma_f32_32x32x16_bf16 v[34:49], v[140:143], v[184:187], v[34:49]
	v_cvt_pk_bf16_f32 v215, v77, v78
	v_cvt_pk_bf16_f32 v216, v79, v80
	v_cvt_pk_bf16_f32 v217, v81, v82
	s_andn2_b64 vcc, exec, s[10:11]
	s_waitcnt lgkmcnt(7)
	v_mfma_f32_32x32x16_bf16 v[18:33], v[144:147], v[184:187], v[18:33]
	s_waitcnt lgkmcnt(5)
	v_mfma_f32_32x32x16_bf16 v[2:17], v[132:135], v[184:187], v[2:17]
	v_mfma_f32_32x32x16_bf16 v[50:65], v[116:119], v[214:217], v[50:65]
	v_mfma_f32_32x32x16_bf16 v[34:49], v[120:123], v[214:217], v[34:49]
	v_mfma_f32_32x32x16_bf16 v[18:33], v[124:127], v[214:217], v[18:33]
	s_waitcnt lgkmcnt(4)
	v_mfma_f32_32x32x16_bf16 v[2:17], v[128:131], v[214:217], v[2:17]
.LBB0_414:
	v_add_f32_e32 v67, 0, v67
	v_add_f32_e32 v67, v68, v67
	v_add_f32_e32 v67, v69, v67
	v_add_f32_e32 v67, v70, v67
	v_add_f32_e32 v67, v71, v67
	v_add_f32_e32 v67, v72, v67
	v_add_f32_e32 v67, v73, v67
	v_add_f32_e32 v67, v74, v67
	v_add_f32_e32 v67, v75, v67
	v_add_f32_e32 v67, v76, v67
	v_add_f32_e32 v67, v77, v67
	v_add_f32_e32 v67, v78, v67
	v_add_f32_e32 v67, v79, v67
	v_add_f32_e32 v67, v80, v67
	v_add_f32_e32 v67, v81, v67
	v_add_f32_e32 v67, v82, v67
	s_mov_b64 s[10:11], 0x2000
	v_add_f32_e32 v171, v171, v67
	v_lshl_add_u64 v[172:173], v[172:173], 0, s[10:11]
	s_cmp_eq_u32 s7, s14
	v_lshl_add_u64 v[174:175], v[174:175], 0, s[94:95]
	s_cbranch_scc1 .LBB0_416
	s_mov_b32 s15, s14
	s_branch .LBB0_406
